# speedup vs baseline: 1.0141x; 1.0033x over previous
; #define SLOAD(i, k0) do { const unsigned o0_ = soff0 + (unsigned)(k0) * (DM * 2u), o1_ = o0_ + 32u * DM * 2u;                 \
;     sr_[i].vs0 = *(const bf16x8*)((const char*)Vh + (size_t)o0_); sr_[i].vs1 = *(const bf16x8*)((const char*)Vh + (size_t)o1_); \
;     sr_[i].ks0 = *(const bf16x8*)((const char*)Kh + (size_t)o0_); sr_[i].ks1 = *(const bf16x8*)((const char*)Kh + (size_t)o1_); } while (0)
; #define SWRITE(boff, i) do { *(bf16x8*)(V_lds + (boff) + vst0) = sr_[i].vs0;          \
;     *(bf16x8*)(V_lds + (boff) + vst1) = sr_[i].vs1; int kc = sc * 2;               \
;     *(bf16x8*)(K_lds + (boff) + KSWZ(sr, kc)) = sr_[i].ks0;                       \
;     *(bf16x8*)(K_lds + (boff) + KSWZ(32 + sr, kc)) = sr_[i].ks1; } while (0)
; __device__ __forceinline__ void da_qkt(f32x16& p0, f32x16& p1, const char* Ks, const bf16x8* qr, int r32, int hi, int cbyte0) {
;   p0 = f32x16{}; p1 = f32x16{};
; #pragma unroll
;   for (int d0 = 0; d0 < 4; ++d0) {
;     int cbb = cbyte0 + (d0 * 16 + hi * 8) * 2;
;     bf16x8 b0 = *(const bf16x8*)(Ks + KSWZ(r32, cbb));
;     bf16x8 b1 = *(const bf16x8*)(Ks + KSWZ(32 + r32, cbb));
;     p0 = __builtin_amdgcn_mfma_f32_32x32x16_bf16(b0, qr[d0], p0, 0, 0, 0);
;     p1 = __builtin_amdgcn_mfma_f32_32x32x16_bf16(b1, qr[d0], p1, 0, 0, 0);
;   }
; }
; __device__ __forceinline__ void diff_block(const Params& p, int s, int h, int qb, char* lds, float lam_full, u16* Odst) {
;     ...
;   {
;     const bf16x8 zero8 = {0, 0, 0, 0, 0, 0, 0, 0};
;     sr_[SO].vs0 = zero8; sr_[SO].vs1 = zero8; sr_[SO].ks0 = zero8; sr_[SO].ks1 = zero8;
;     if (sr < 16) {
;       sr_[SO].ks0 = *(const bf16x8*)(Kp + (long)(NREAL + sr) * DM + h * 128 + sc);
;       sr_[SO].vs0 = *(const bf16x8*)(Vp + (long)(NREAL + sr) * DM + h * 128 + sc);
;     }
;     SLOAD(SE, 0);
;     __syncthreads();
;     SWRITE(2 * SHM_V, SO);
;     __syncthreads();
;     da_qkt(pA0, pA1, K_lds + 2 * SHM_K, qr, r32, hi, cbyte0);
; #pragma unroll
;     for (int r = 8; r < 16; ++r) pA0[r] = -1e30f;
; #pragma unroll
;     for (int r = 0; r < 16; ++r) pA1[r] = -1e30f;
;     da_partialSM(pA0, pA1, m_reg, mnA, alA);
;     da_finishSM(pA0, pA1, alA, l_reg, pa0, pa1, pa2, pa3);
;     da_pv(o, vb0 + 2 * SHM_V, pa0, pa1, pa2, pa3);
.LBB0_233:
	s_or_b64 exec, exec, s[2:3]
	v_and_b32_e32 v9, 0xfffff0, v8
	v_lshlrev_b32_e32 v11, 1, v8
	v_and_or_b32 v9, v11, 8, v9
	s_ashr_i32 s1, s0, 31
	v_lshrrev_b32_e32 v11, 1, v8
	v_lshrrev_b32_e32 v9, 1, v9
	v_lshrrev_b32_e32 v10, 5, v10
	v_and_b32_e32 v12, 3, v8
	s_lshl_b64 s[0:1], s[0:1], 11
	v_readlane_b32 s2, v254, 14
	v_or_b32_e32 v9, v9, v10
	v_and_or_b32 v11, v11, 4, v12
	v_readlane_b32 s3, v254, 15
	s_add_u32 s2, s2, s0
	v_lshlrev_b32_e32 v9, 9, v9
	v_lshlrev_b32_e32 v11, 6, v11
	v_and_b32_e32 v12, 48, v130
	s_addc_u32 s3, s3, s1
	v_or3_b32 v216, v9, v11, v12
	v_add_u32_e32 v9, 32, v8
	s_add_u32 s2, s2, s24
	v_and_b32_e32 v13, 0xfffff0, v9
	v_lshlrev_b32_e32 v14, 1, v9
	s_addc_u32 s3, s3, 0
	v_readlane_b32 s4, v254, 16
	v_and_or_b32 v13, v14, 8, v13
	v_readlane_b32 s5, v254, 17
	s_add_u32 s0, s4, s0
	v_lshrrev_b32_e32 v13, 1, v13
	s_addc_u32 s1, s5, s1
	v_or_b32_e32 v10, v13, v10
	s_add_u32 s8, s0, s24
	v_lshlrev_b32_e32 v131, 11, v8
	v_lshlrev_b32_e32 v10, 9, v10
	s_addc_u32 s9, s1, 0
	v_or_b32_e32 v118, v130, v131
	v_or3_b32 v217, v10, v11, v12
	v_add_u32_e32 v10, 0x10000, v118
	global_load_dwordx4 v[64:67], v118, s[8:9]
	global_load_dwordx4 v[68:71], v118, s[2:3]
	global_load_dwordx4 v[76:79], v10, s[8:9]
	global_load_dwordx4 v[72:75], v10, s[2:3]
	s_barrier
	s_waitcnt vmcnt(4)
	ds_write_b128 v216, v[4:7] offset:32768
	s_mov_b32 s6, s25
	s_mov_b32 s7, s25
	v_lshlrev_b32_e32 v4, 8, v8
	v_and_b32_e32 v5, 0x70, v115
	s_mov_b32 s4, s25
	s_mov_b32 s5, s25
	v_mov_b64_e32 v[12:13], s[6:7]
	v_bitop3_b32 v221, v130, v4, v5 bitop3:0xde
	v_mov_b64_e32 v[10:11], s[4:5]
	v_add_u32_e32 v4, 0x14000, v221
	ds_write_b128 v217, v[10:13] offset:32768
	ds_write_b128 v4, v[0:3]
	v_lshlrev_b32_e32 v0, 8, v9
	v_bitop3_b32 v222, v130, v0, v5 bitop3:0xde
	v_add_u32_e32 v0, 0x14000, v222
	ds_write_b128 v0, v[10:13]
	v_and_b32_e32 v229, 0x13, v207
	v_and_b32_e32 v230, 4, v207
	v_lshl_or_b32 v229, v230, 1, v229
	v_and_b32_e32 v230, 8, v207
	v_lshrrev_b32_e32 v230, 1, v230
	v_or_b32_e32 v229, v229, v230
	v_lshlrev_b32_e32 v0, 4, v229
	v_lshl_or_b32 v20, v211, 7, v96
	v_lshlrev_b32_e32 v21, 8, v229
	v_and_b32_e32 v22, 0x70, v0
	v_bitop3_b32 v223, v20, v21, v22 bitop3:0xde
	v_or_b32_e32 v0, 0x14000, v223
	s_waitcnt lgkmcnt(0)
	s_barrier
	ds_read_b128 v[0:3], v0
	v_or_b32_e32 v4, 32, v20
	v_bitop3_b32 v220, v4, v21, v22 bitop3:0xde
	v_or_b32_e32 v4, 0x14000, v220
	ds_read_b128 v[16:19], v4
	s_waitcnt lgkmcnt(1)
	v_mfma_f32_32x32x16_bf16 v[0:15], v[0:3], v[110:113], 0
	s_mov_b32 s0, 0xf149f2ca
	v_and_b32_e32 v132, 63, v115
	v_lshlrev_b32_e32 v24, 3, v132
	s_waitcnt lgkmcnt(0)
	v_mfma_f32_32x32x16_bf16 v[0:15], v[16:19], v[106:109], v[0:15]
	v_or_b32_e32 v16, 64, v20
	v_bitop3_b32 v219, v16, v21, v22 bitop3:0xde
	v_or_b32_e32 v16, 0x14000, v219
	ds_read_b128 v[16:19], v16
	v_or_b32_e32 v20, 0x60, v20
	v_bitop3_b32 v218, v20, v21, v22 bitop3:0xde
	v_or_b32_e32 v20, 0x14000, v218
	ds_read_b128 v[20:23], v20
	s_waitcnt lgkmcnt(1)
	v_mfma_f32_32x32x16_bf16 v[0:15], v[16:19], v[102:105], v[0:15]
	v_lshlrev_b32_e32 v16, 4, v132
	v_and_b32_e32 v16, 0xc0, v16
	v_lshlrev_b32_e32 v17, 1, v132
	v_and_or_b32 v16, v24, 24, v16
	v_and_b32_e32 v17, 32, v17
	v_and_b32_e32 v18, 0x100, v24
	v_or3_b32 v214, v16, v17, v18
	s_waitcnt lgkmcnt(0)
	v_mfma_f32_32x32x16_bf16 v[0:15], v[20:23], v[98:101], v[0:15]
	v_or_b32_e32 v128, 0x8000, v214
	s_nop 10
	v_max3_f32 v8, v0, v1, v2
	v_max3_f32 v8, v8, v3, v4
	v_max3_f32 v8, v8, v5, v6
	v_max3_f32 v8, v8, v7, s0
	v_mov_b32_e32 v9, v8
	s_nop 1
	v_permlane32_swap_b32_e32 v8, v9
	v_max_f32_e32 v9, v9, v9
	v_max_f32_e32 v8, v8, v8
	v_max_f32_e32 v8, v8, v9
	v_add_f32_e32 v9, 0x7149f2ca, v8
	s_mov_b32 s0, 0x42800000
	v_cmp_ge_f32_e32 vcc, s0, v9
	s_cmp_eq_u64 vcc, exec
	v_max_f32_e32 v116, 0xf149f2ca, v8
	s_cselect_b64 s[6:7], -1, 0
	v_cndmask_b32_e64 v213, v116, v194, s[6:7]
	v_mul_f32_e32 v114, 0xbe38aa3b, v213
	v_fmamk_f32 v0, v0, 0x3e38aa3b, v114
	v_fmamk_f32 v1, v1, 0x3e38aa3b, v114
	v_exp_f32_e32 v0, v0
	v_fmamk_f32 v2, v2, 0x3e38aa3b, v114
	v_exp_f32_e32 v1, v1
	v_fmamk_f32 v3, v3, 0x3e38aa3b, v114
	v_exp_f32_e32 v2, v2
	v_fmamk_f32 v4, v4, 0x3e38aa3b, v114
	v_exp_f32_e32 v3, v3
	v_fmamk_f32 v5, v5, 0x3e38aa3b, v114
	v_exp_f32_e32 v4, v4
	v_add_f32_e32 v9, 0, v0
	v_fmamk_f32 v6, v6, 0x3e38aa3b, v114
	v_exp_f32_e32 v5, v5
	v_add_f32_e32 v9, v1, v9
	v_fmamk_f32 v7, v7, 0x3e38aa3b, v114
	v_mov_b32_e32 v8, 0x3e38aa3b
	v_exp_f32_e32 v6, v6
	v_add_f32_e32 v9, v2, v9
	v_fmamk_f32 v8, v8, 0xf149f2ca, v114
	v_exp_f32_e32 v7, v7
	v_add_f32_e32 v9, v3, v9
	v_exp_f32_e32 v8, v8
	v_add_f32_e32 v9, v4, v9
	v_add_f32_e32 v9, v5, v9
	v_add_f32_e32 v9, v6, v9
	v_add_f32_e32 v9, v7, v9
	v_add_f32_e32 v9, v8, v9
	v_add_f32_e32 v9, v8, v9
	v_add_f32_e32 v9, v8, v9
	v_add_f32_e32 v9, v8, v9
	v_add_f32_e32 v9, v8, v9
	v_add_f32_e32 v9, v8, v9
	v_add_f32_e32 v9, v8, v9
	v_add_f32_e32 v9, v8, v9
	v_add_f32_e32 v9, v8, v9
	v_add_f32_e32 v9, v8, v9
	v_add_f32_e32 v9, v8, v9
	v_add_f32_e32 v9, v8, v9
	v_add_f32_e32 v9, v8, v9
	v_add_f32_e32 v9, v8, v9
	v_add_f32_e32 v9, v8, v9
	v_add_f32_e32 v9, v8, v9
	v_cvt_pk_bf16_f32 v48, v0, v1
	v_cvt_pk_bf16_f32 v49, v2, v3
	v_cvt_pk_bf16_f32 v50, v4, v5
	v_cvt_pk_bf16_f32 v51, v6, v7
	v_cvt_pk_bf16_f32 v80, v8, v8
	v_cvt_pk_bf16_f32 v81, v8, v8
	v_cvt_pk_bf16_f32 v82, v8, v8
	v_cvt_pk_bf16_f32 v83, v8, v8
	v_cvt_pk_bf16_f32 v84, v8, v8
	v_cvt_pk_bf16_f32 v85, v8, v8
	v_cvt_pk_bf16_f32 v86, v8, v8
	v_cvt_pk_bf16_f32 v87, v8, v8
	v_cvt_pk_bf16_f32 v88, v8, v8
	v_cvt_pk_bf16_f32 v89, v8, v8
	v_cvt_pk_bf16_f32 v90, v8, v8
	v_cvt_pk_bf16_f32 v91, v8, v8
	ds_read_b64_tr_b16 v[0:1], v128 offset:0
	v_add_f32_e32 v9, v8, v9
	ds_read_b64_tr_b16 v[2:3], v128 offset:0x800
	v_add_f32_e32 v9, v8, v9
	ds_read_b64_tr_b16 v[16:17], v128 offset:0x1000
	v_add_f32_e32 v9, v8, v9
	ds_read_b64_tr_b16 v[18:19], v128 offset:0x1800
	v_add_f32_e32 v9, v8, v9
	ds_read_b64_tr_b16 v[20:21], v128 offset:0x2000
	v_add_f32_e32 v9, v8, v9
	ds_read_b64_tr_b16 v[22:23], v128 offset:0x2800
	v_add_f32_e32 v9, v8, v9
	ds_read_b64_tr_b16 v[24:25], v128 offset:0x3000
	v_add_f32_e32 v9, v8, v9
	ds_read_b64_tr_b16 v[26:27], v128 offset:0x3800
	v_add_f32_e32 v117, v8, v9
	s_waitcnt lgkmcnt(0)
; #define SWRITE(boff, i) do { *(bf16x8*)(V_lds + (boff) + vst0) = sr_[i].vs0;          \
;     *(bf16x8*)(V_lds + (boff) + vst1) = sr_[i].vs1; int kc = sc * 2;               \
;     *(bf16x8*)(K_lds + (boff) + KSWZ(sr, kc)) = sr_[i].ks0;                       \
;     *(bf16x8*)(K_lds + (boff) + KSWZ(32 + sr, kc)) = sr_[i].ks1; } while (0)
; __device__ __forceinline__ void da_finishSM(f32x16& p0, f32x16& p1, float alpha, float& l_reg, bf16x8& pa0, bf16x8& pa1, bf16x8& pa2, bf16x8& pa3) {
;     ...
;   { auto rr = __builtin_amdgcn_permlane32_swap(__float_as_uint(ps), __float_as_uint(ps), false, false);
;     ps = __uint_as_float(rr[0]) + __uint_as_float(rr[1]); }
;   l_reg = l_reg * alpha + ps;
; __device__ __forceinline__ void diff_block(const Params& p, int s, int h, int qb, char* lds, float lam_full, u16* Odst) {
;     ...
;     da_pv(o, vb0 + 2 * SHM_V, pa0, pa1, pa2, pa3);
;   }
;   asm volatile("s_waitcnt vmcnt(0)" ::: "memory"); SWRITE(0, SE); __syncthreads();
;   da_qkt(pA0, pA1, K_lds, qr, r32, hi, cbyte0); da_partialSM(pA0, pA1, m_reg, mnA, alA);
	v_mfma_f32_32x32x16_bf16 v[0:15], v[48:51], v[0:3], 0
	v_mfma_f32_32x32x16_bf16 v[0:15], v[80:83], v[16:19], v[0:15]
	ds_read_b64_tr_b16 v[16:17], v128 offset:0x200
	ds_read_b64_tr_b16 v[18:19], v128 offset:0xa00
	ds_read_b64_tr_b16 v[32:33], v128 offset:0x1200
	ds_read_b64_tr_b16 v[34:35], v128 offset:0x1a00
	ds_read_b64_tr_b16 v[36:37], v128 offset:0x2200
	ds_read_b64_tr_b16 v[38:39], v128 offset:0x2a00
	ds_read_b64_tr_b16 v[40:41], v128 offset:0x3200
	v_mfma_f32_32x32x16_bf16 v[0:15], v[84:87], v[20:23], v[0:15]
	ds_read_b64_tr_b16 v[42:43], v128 offset:0x3a00
	s_waitcnt lgkmcnt(0)
	v_mfma_f32_32x32x16_bf16 v[0:15], v[88:91], v[24:27], v[0:15]
	v_mfma_f32_32x32x16_bf16 v[16:31], v[48:51], v[16:19], 0
	v_mfma_f32_32x32x16_bf16 v[16:31], v[80:83], v[32:35], v[16:31]
	ds_read_b64_tr_b16 v[32:33], v128 offset:0x400
	ds_read_b64_tr_b16 v[34:35], v128 offset:0xc00
	ds_read_b64_tr_b16 v[52:53], v128 offset:0x1400
	ds_read_b64_tr_b16 v[54:55], v128 offset:0x1c00
	ds_read_b64_tr_b16 v[56:57], v128 offset:0x2400
	ds_read_b64_tr_b16 v[58:59], v128 offset:0x2c00
	ds_read_b64_tr_b16 v[60:61], v128 offset:0x3400
	v_mfma_f32_32x32x16_bf16 v[16:31], v[84:87], v[36:39], v[16:31]
	ds_read_b64_tr_b16 v[62:63], v128 offset:0x3c00
	s_waitcnt lgkmcnt(0)
	v_mfma_f32_32x32x16_bf16 v[16:31], v[88:91], v[40:43], v[16:31]
	v_mfma_f32_32x32x16_bf16 v[32:47], v[48:51], v[32:35], 0
	v_mfma_f32_32x32x16_bf16 v[32:47], v[80:83], v[52:55], v[32:47]
	ds_read_b64_tr_b16 v[52:53], v128 offset:0x600
	ds_read_b64_tr_b16 v[54:55], v128 offset:0xe00
	ds_read_b64_tr_b16 v[92:93], v128 offset:0x1600
	ds_read_b64_tr_b16 v[94:95], v128 offset:0x1e00
	ds_read_b64_tr_b16 v[120:121], v128 offset:0x2600
	ds_read_b64_tr_b16 v[122:123], v128 offset:0x2e00
	ds_read_b64_tr_b16 v[124:125], v128 offset:0x3600
	v_mfma_f32_32x32x16_bf16 v[32:47], v[84:87], v[56:59], v[32:47]
	ds_read_b64_tr_b16 v[126:127], v128 offset:0x3e00
	s_waitcnt lgkmcnt(0)
	v_mfma_f32_32x32x16_bf16 v[32:47], v[88:91], v[60:63], v[32:47]
	v_mfma_f32_32x32x16_bf16 v[48:63], v[48:51], v[52:55], 0
	s_waitcnt vmcnt(0)
	s_waitcnt vmcnt(3)
	ds_write_b128 v216, v[64:67]
	s_waitcnt vmcnt(1)
	ds_write_b128 v217, v[76:79]
	ds_write_b128 v221, v[68:71] offset:49152
	s_waitcnt vmcnt(0)
	ds_write_b128 v222, v[72:75] offset:49152
	s_waitcnt lgkmcnt(0)
	s_barrier
	ds_read_b128 v[64:67], v223 offset:49152
	ds_read_b128 v[68:71], v223 offset:57344
	v_mfma_f32_32x32x16_bf16 v[48:63], v[80:83], v[92:95], v[48:63]
	v_mfma_f32_32x32x16_bf16 v[48:63], v[84:87], v[120:123], v[48:63]
	v_mfma_f32_32x32x16_bf16 v[48:63], v[88:91], v[124:127], v[48:63]
	ds_read_b128 v[120:123], v220 offset:49152
	ds_read_b128 v[124:127], v220 offset:57344
	s_waitcnt lgkmcnt(3)
	v_mfma_f32_32x32x16_bf16 v[80:95], v[64:67], v[110:113], 0
	s_waitcnt lgkmcnt(2)
	v_mfma_f32_32x32x16_bf16 v[64:79], v[68:71], v[110:113], 0
	s_waitcnt lgkmcnt(1)
	v_mfma_f32_32x32x16_bf16 v[80:95], v[120:123], v[106:109], v[80:95]
	s_waitcnt lgkmcnt(0)
	v_mfma_f32_32x32x16_bf16 v[64:79], v[124:127], v[106:109], v[64:79]
	ds_read_b128 v[120:123], v219 offset:49152
	ds_read_b128 v[124:127], v219 offset:57344
	s_waitcnt lgkmcnt(1)
	v_mfma_f32_32x32x16_bf16 v[80:95], v[120:123], v[102:105], v[80:95]
	s_waitcnt lgkmcnt(0)
	v_mfma_f32_32x32x16_bf16 v[64:79], v[124:127], v[102:105], v[64:79]
	ds_read_b128 v[120:123], v218 offset:49152
	ds_read_b128 v[124:127], v218 offset:57344
	s_waitcnt lgkmcnt(1)
	v_mfma_f32_32x32x16_bf16 v[80:95], v[120:123], v[98:101], v[80:95]
	s_waitcnt lgkmcnt(0)
	v_mfma_f32_32x32x16_bf16 v[64:79], v[124:127], v[98:101], v[64:79]
	s_nop 9
	v_max_f32_e32 v120, v81, v81
	v_max_f32_e32 v121, v80, v80
	v_max_f32_e32 v120, v121, v120
	v_max3_f32 v120, v120, v82, v83
	v_max3_f32 v120, v120, v84, v85
	v_max3_f32 v120, v120, v86, v87
	v_max3_f32 v120, v120, v88, v89
	v_max3_f32 v120, v120, v90, v91
	v_max3_f32 v120, v120, v92, v93
	v_max3_f32 v120, v120, v94, v95
	v_max3_f32 v120, v120, v64, v65
	v_max3_f32 v120, v120, v66, v67
	v_max3_f32 v120, v120, v68, v69
	v_max3_f32 v120, v120, v70, v71
	v_max3_f32 v120, v120, v72, v73
	v_max3_f32 v120, v120, v74, v75
	v_max3_f32 v120, v120, v76, v77
	v_max3_f32 v120, v120, v78, v79
	v_mov_b32_e32 v121, v120
	s_nop 1
	v_permlane32_swap_b32_e32 v120, v121
	v_max_f32_e32 v121, v121, v121
	v_max_f32_e32 v120, v120, v120
	v_max_f32_e32 v121, v120, v121
	v_sub_f32_e32 v120, v121, v213
	v_cmp_ge_f32_e32 vcc, s0, v120
	v_mov_b32_e32 v120, 1.0
	s_cmp_eq_u64 vcc, exec
	s_cbranch_scc0 .LBB0_274

; #define SBAR() __builtin_amdgcn_sched_barrier(0)
; #define SLOAD(i, k0) do { const unsigned o0_ = soff0 + (unsigned)(k0) * (DM * 2u), o1_ = o0_ + 32u * DM * 2u;                 \
;     sr_[i].vs0 = *(const bf16x8*)((const char*)Vh + (size_t)o0_); sr_[i].vs1 = *(const bf16x8*)((const char*)Vh + (size_t)o1_); \
;     sr_[i].ks0 = *(const bf16x8*)((const char*)Kh + (size_t)o0_); sr_[i].ks1 = *(const bf16x8*)((const char*)Kh + (size_t)o1_); } while (0)
; #define SWRITE(boff, i) do { *(bf16x8*)(V_lds + (boff) + vst0) = sr_[i].vs0;          \
;     *(bf16x8*)(V_lds + (boff) + vst1) = sr_[i].vs1; int kc = sc * 2;               \
;     *(bf16x8*)(K_lds + (boff) + KSWZ(sr, kc)) = sr_[i].ks0;                       \
;     *(bf16x8*)(K_lds + (boff) + KSWZ(32 + sr, kc)) = sr_[i].ks1; } while (0)
; #define SWAIT() asm volatile("s_waitcnt vmcnt(4)" ::: "memory")
; __device__ __forceinline__ void da_finish2(f32x16& p0, f32x16& p1, float& m_reg, float& l_reg, float& alpha,
;                                            bf16x8& pa0, bf16x8& pa1, bf16x8& pa2, bf16x8& pa3) {
;     ...
;   for (int r = 0; r < 16; ++r) p1[r] = __builtin_amdgcn_exp2f(p1[r]);
;   float ps = 0.f;
; #pragma unroll
;   for (int r = 0; r < 16; ++r) ps += p0[r];
; #pragma unroll
;   for (int r = 0; r < 16; ++r) ps += p1[r];
;   { auto rr = __builtin_amdgcn_permlane32_swap(__float_as_uint(ps), __float_as_uint(ps), false, false);
;     ps = __uint_as_float(rr[0]) + __uint_as_float(rr[1]); }
;   alpha = 1.f;
;   if (__builtin_expect(!__all(ps < DA_BIG), 0)) {
; __device__ __forceinline__ void diff_block(const Params& p, int s, int h, int qb, char* lds, float lam_full, u16* Odst) {
;     ...
;   asm volatile("s_waitcnt vmcnt(0)" ::: "memory"); SWRITE(0, SE); __syncthreads();
;   da_qkt(pA0, pA1, K_lds, qr, r32, hi, cbyte0); da_partialSM(pA0, pA1, m_reg, mnA, alA);
;   RESC(alA);
;   SLOAD(SO, 64); if (2 < NT) SLOAD(SE, 128);
;   SWAIT(); SWRITE(SHM_V, SO); __syncthreads();
;   int pV = 0, cK = SHM_V, nW = 2 * SHM_V;
;   for (int j = 1; j + 1 < NT; j += 2) {
;     SBAR(); da_qkt(pB0, pB1, K_lds + cK, qr, r32, hi, cbyte0);
;     da_finish2(pA0, pA1, m_reg, l_reg, alA, pa0, pa1, pa2, pa3); SBAR();
;     RESC(alA);
;     SLOAD(SO, (j + 2) * 64); SBAR();
;     da_pv(o, vb0 + pV, pa0, pa1, pa2, pa3); da_partial2(pB0, pB1, m_reg);
;     SWAIT(); SWRITE(nW, SE);
.LBB0_238:
	v_sub_f32_e32 v115, 0xf149f2ca, v116
	v_mul_f32_e32 v115, 0x3e38aa3b, v115
	v_exp_f32_e32 v115, v115
	v_fmamk_f32 v80, v80, 0x3e38aa3b, v114
	v_fmamk_f32 v81, v81, 0x3e38aa3b, v114
	v_mov_b32_e32 v116, v114
	v_pk_fma_f32 v[176:177], v[64:65], s[20:21], v[114:115] op_sel_hi:[1,0,0]
	v_mul_f32_e32 v65, 0, v115
	v_fmac_f32_e32 v116, 0x3e38aa3b, v95
	v_pk_fma_f32 v[166:167], v[76:77], s[20:21], v[114:115] op_sel_hi:[1,0,0]
	v_pk_fma_f32 v[170:171], v[72:73], s[20:21], v[114:115] op_sel_hi:[1,0,0]
	v_exp_f32_e32 v146, v80
	v_exp_f32_e32 v147, v81
	v_mov_b32_e32 v64, v117
	v_cndmask_b32_e64 v65, v65, 0, s[6:7]
	v_add_u32_e32 v72, 0x20000, v118
	v_add_u32_e32 v76, 0x30000, v118
	v_add_u32_e32 v80, 0x50000, v118
	v_add_u32_e32 v81, 0x40000, v118
	v_fmamk_f32 v82, v82, 0x3e38aa3b, v114
	v_fmamk_f32 v83, v83, 0x3e38aa3b, v114
	v_fmamk_f32 v84, v84, 0x3e38aa3b, v114
	v_fmamk_f32 v85, v85, 0x3e38aa3b, v114
	v_fmamk_f32 v86, v86, 0x3e38aa3b, v114
	v_fmamk_f32 v87, v87, 0x3e38aa3b, v114
	v_fmamk_f32 v88, v88, 0x3e38aa3b, v114
	v_fmamk_f32 v89, v89, 0x3e38aa3b, v114
	v_fmamk_f32 v90, v90, 0x3e38aa3b, v114
	v_fmamk_f32 v91, v91, 0x3e38aa3b, v114
	v_fmamk_f32 v92, v92, 0x3e38aa3b, v114
	v_fmamk_f32 v93, v93, 0x3e38aa3b, v114
	v_fmamk_f32 v94, v94, 0x3e38aa3b, v114
	v_pk_fma_f32 v[164:165], v[78:79], s[20:21], v[114:115] op_sel_hi:[1,0,0]
	v_pk_fma_f32 v[168:169], v[74:75], s[20:21], v[114:115] op_sel_hi:[1,0,0]
	v_pk_fma_f32 v[174:175], v[70:71], s[20:21], v[114:115] op_sel_hi:[1,0,0]
	v_pk_fma_f32 v[178:179], v[68:69], s[20:21], v[114:115] op_sel_hi:[1,0,0]
	v_pk_fma_f32 v[172:173], v[66:67], s[20:21], v[114:115] op_sel_hi:[1,0,0]
	v_exp_f32_e32 v155, v116
	v_add_f32_e32 v226, v64, v65
	global_load_dwordx4 v[64:67], v72, s[8:9]
	global_load_dwordx4 v[68:71], v76, s[8:9]
	s_nop 0
	global_load_dwordx4 v[72:75], v72, s[2:3]
	s_nop 0
	global_load_dwordx4 v[76:79], v76, s[2:3]
	v_exp_f32_e32 v148, v82
	global_load_dwordx4 v[114:117], v80, s[2:3]
	global_load_dwordx4 v[118:121], v81, s[2:3]
	global_load_dwordx4 v[122:125], v80, s[8:9]
	global_load_dwordx4 v[126:129], v81, s[8:9]
	v_exp_f32_e32 v149, v83
	v_exp_f32_e32 v150, v84
	v_exp_f32_e32 v151, v85
	v_exp_f32_e32 v160, v86
	v_exp_f32_e32 v161, v87
	v_exp_f32_e32 v158, v88
	v_exp_f32_e32 v159, v89
	v_exp_f32_e32 v156, v90
	v_exp_f32_e32 v157, v91
	v_exp_f32_e32 v152, v92
	v_exp_f32_e32 v153, v93
	v_exp_f32_e32 v154, v94
	s_and_b64 s[0:1], s[10:11], exec
	s_waitcnt vmcnt(4)
	s_cselect_b32 s5, 64, 0x80
	s_mov_b32 s0, 0x90000
	s_add_i32 s11, s5, -1
	v_cmp_gt_u32_e64 s[6:7], 32, v132
	v_lshl_add_u32 v215, v207, 2, v212
	v_add3_u32 v227, v131, v130, s0
	s_mov_b32 s10, 0
	s_movk_i32 s12, 0x4000
	s_mov_b32 s0, 0x8000
	s_mov_b32 s13, 4
	s_waitcnt vmcnt(7)
	ds_write_b128 v216, v[64:67] offset:16384
	s_waitcnt vmcnt(6)
	ds_write_b128 v217, v[68:71] offset:16384
	v_add_u32_e32 v64, 0x10000, v221
	s_waitcnt vmcnt(5)
	ds_write_b128 v64, v[72:75]
	v_add_u32_e32 v64, 0x10000, v222
	s_waitcnt vmcnt(4)
	ds_write_b128 v64, v[76:79]
	s_waitcnt lgkmcnt(0)
	s_barrier
.LBB0_239:
	s_mov_b32 s4, s0
	v_add_u32_e32 v68, s12, v223
	ds_read_b128 v[64:67], v68 offset:49152
	ds_read_b128 v[68:71], v68 offset:57344
	v_add_u32_e32 v134, s12, v220
	ds_read_b128 v[130:133], v134 offset:49152
	ds_read_b128 v[134:137], v134 offset:57344
	v_exp_f32_e32 v144, v164
	s_waitcnt lgkmcnt(3)
	v_mfma_f32_32x32x16_bf16 v[80:95], v[64:67], v[110:113], 0
	v_add_f32_e32 v164, 0, v146
	v_add_f32_e32 v164, v147, v164
	v_add_f32_e32 v164, v148, v164
	v_add_f32_e32 v164, v149, v164
	v_add_f32_e32 v164, v150, v164
	v_add_f32_e32 v164, v151, v164
	v_add_f32_e32 v164, v160, v164
	s_waitcnt lgkmcnt(2)
	v_mfma_f32_32x32x16_bf16 v[64:79], v[68:71], v[110:113], 0
	v_add_f32_e32 v164, v161, v164
	v_add_f32_e32 v164, v158, v164
	v_add_f32_e32 v164, v159, v164
	v_add_f32_e32 v164, v156, v164
	v_add_f32_e32 v164, v157, v164
	v_add_f32_e32 v164, v152, v164
	v_add_f32_e32 v164, v153, v164
	s_waitcnt lgkmcnt(1)
	v_mfma_f32_32x32x16_bf16 v[80:95], v[130:133], v[106:109], v[80:95]
	v_add_f32_e32 v164, v154, v164
	v_add_f32_e32 v164, v155, v164
	v_exp_f32_e32 v138, v174
	v_exp_f32_e32 v139, v175
	v_exp_f32_e32 v140, v168
	v_exp_f32_e32 v141, v169
	v_exp_f32_e32 v142, v166
	s_waitcnt lgkmcnt(0)
	v_mfma_f32_32x32x16_bf16 v[64:79], v[134:137], v[106:109], v[64:79]
	v_add_u32_e32 v134, s12, v219
	ds_read_b128 v[130:133], v134 offset:49152
	ds_read_b128 v[134:137], v134 offset:57344
	v_exp_f32_e32 v143, v167
	v_exp_f32_e32 v145, v165
	s_waitcnt lgkmcnt(1)
	v_mfma_f32_32x32x16_bf16 v[80:95], v[130:133], v[102:105], v[80:95]
	s_waitcnt lgkmcnt(0)
	v_mfma_f32_32x32x16_bf16 v[64:79], v[134:137], v[102:105], v[64:79]
	v_add_u32_e32 v134, s12, v218
	ds_read_b128 v[130:133], v134 offset:49152
	ds_read_b128 v[134:137], v134 offset:57344
	s_waitcnt lgkmcnt(1)
	v_mfma_f32_32x32x16_bf16 v[80:95], v[130:133], v[98:101], v[80:95]
	v_exp_f32_e32 v130, v176
	v_exp_f32_e32 v131, v177
	v_exp_f32_e32 v132, v172
	v_exp_f32_e32 v133, v173
	v_add_f32_e32 v164, v130, v164
	v_add_f32_e32 v164, v131, v164
	v_add_f32_e32 v164, v132, v164
	s_waitcnt lgkmcnt(0)
	v_mfma_f32_32x32x16_bf16 v[64:79], v[134:137], v[98:101], v[64:79]
	v_exp_f32_e32 v134, v178
	v_exp_f32_e32 v135, v179
	v_add_f32_e32 v164, v133, v164
	v_exp_f32_e32 v136, v170
	v_add_f32_e32 v164, v134, v164
	v_exp_f32_e32 v137, v171
	v_add_f32_e32 v164, v135, v164
	v_add_f32_e32 v164, v138, v164
	v_add_f32_e32 v164, v139, v164
	v_add_f32_e32 v164, v136, v164
	v_add_f32_e32 v164, v137, v164
	v_add_f32_e32 v164, v140, v164
	v_add_f32_e32 v164, v141, v164
	v_add_f32_e32 v164, v142, v164
	v_add_f32_e32 v164, v143, v164
	v_add_f32_e32 v164, v144, v164
	v_add_f32_e32 v165, v145, v164
	v_cmp_gt_f32_e32 vcc, s34, v165
	s_cmp_eq_u64 vcc, exec
	v_mov_b32_e32 v164, 1.0
	s_cbranch_scc0 .LBB0_254

; #define SBAR() __builtin_amdgcn_sched_barrier(0)
; #define SLOAD(i, k0) do { const unsigned o0_ = soff0 + (unsigned)(k0) * (DM * 2u), o1_ = o0_ + 32u * DM * 2u;                 \
;     sr_[i].vs0 = *(const bf16x8*)((const char*)Vh + (size_t)o0_); sr_[i].vs1 = *(const bf16x8*)((const char*)Vh + (size_t)o1_); \
;     sr_[i].ks0 = *(const bf16x8*)((const char*)Kh + (size_t)o0_); sr_[i].ks1 = *(const bf16x8*)((const char*)Kh + (size_t)o1_); } while (0)
; #define SWRITE(boff, i) do { *(bf16x8*)(V_lds + (boff) + vst0) = sr_[i].vs0;          \
;     *(bf16x8*)(V_lds + (boff) + vst1) = sr_[i].vs1; int kc = sc * 2;               \
;     *(bf16x8*)(K_lds + (boff) + KSWZ(sr, kc)) = sr_[i].ks0;                       \
;     *(bf16x8*)(K_lds + (boff) + KSWZ(32 + sr, kc)) = sr_[i].ks1; } while (0)
; #define SWAIT() asm volatile("s_waitcnt vmcnt(4)" ::: "memory")
; template <int D0> __device__ __forceinline__ void pv_one(f32x16& od, int vb, bf16x8 pa0, bf16x8 pa1, bf16x8 pa2, bf16x8 pa3) {
;   const s16x4 l0 = tr_read<v_rd_off(D0, 0, 0)>(vb), h0 = tr_read<v_rd_off(D0, 0, 1)>(vb), l1 = tr_read<v_rd_off(D0, 1, 0)>(vb), h1 = tr_read<v_rd_off(D0, 1, 1)>(vb);
;   const s16x4 l2 = tr_read<v_rd_off(D0, 2, 0)>(vb), h2 = tr_read<v_rd_off(D0, 2, 1)>(vb), l3 = tr_read<v_rd_off(D0, 3, 0)>(vb), h3 = tr_read<v_rd_off(D0, 3, 1)>(vb);
;   asm volatile("s_waitcnt lgkmcnt(0)" ::: "memory"); SBAR();
;     ...
;   od = __builtin_amdgcn_mfma_f32_32x32x16_bf16(pa0, PK(l0, h0), od, 0, 0, 0);
;   od = __builtin_amdgcn_mfma_f32_32x32x16_bf16(pa1, PK(l1, h1), od, 0, 0, 0);
;   od = __builtin_amdgcn_mfma_f32_32x32x16_bf16(pa2, PK(l2, h2), od, 0, 0, 0);
;   od = __builtin_amdgcn_mfma_f32_32x32x16_bf16(pa3, PK(l3, h3), od, 0, 0, 0);
; __device__ __forceinline__ void diff_block(const Params& p, int s, int h, int qb, char* lds, float lam_full, u16* Odst) {
;     ...
;     SLOAD(SO, (j + 2) * 64); SBAR();
;     da_pv(o, vb0 + pV, pa0, pa1, pa2, pa3); da_partial2(pB0, pB1, m_reg);
;     SWAIT(); SWRITE(nW, SE);
;     __syncthreads();
.LBB0_244:
	v_add_u32_e32 v130, 0xfffd0000, v227
	v_add_u32_e32 v134, 0xfffe0000, v227
	global_load_dwordx4 v[138:141], v130, s[8:9]
	s_nop 0
	global_load_dwordx4 v[130:133], v130, s[2:3]
	s_nop 0
	global_load_dwordx4 v[142:145], v134, s[8:9]
	s_nop 0
	global_load_dwordx4 v[134:137], v134, s[2:3]
	v_add_u32_e32 v224, s10, v214
	ds_read_b64_tr_b16 v[166:167], v224 offset:0
	ds_read_b64_tr_b16 v[168:169], v224 offset:0x800
	ds_read_b64_tr_b16 v[170:171], v224 offset:0x1000
	ds_read_b64_tr_b16 v[172:173], v224 offset:0x1800
	ds_read_b64_tr_b16 v[174:175], v224 offset:0x2000
	ds_read_b64_tr_b16 v[176:177], v224 offset:0x2800
	ds_read_b64_tr_b16 v[178:179], v224 offset:0x3000
	ds_read_b64_tr_b16 v[180:181], v224 offset:0x3800
	s_waitcnt lgkmcnt(0)
	s_nop 0
	v_mfma_f32_32x32x16_bf16 v[0:15], v[146:149], v[166:169], v[0:15]
	ds_read_b64_tr_b16 v[166:167], v224 offset:0x200
	ds_read_b64_tr_b16 v[168:169], v224 offset:0xa00
	v_mfma_f32_32x32x16_bf16 v[0:15], v[150:153], v[170:173], v[0:15]
	ds_read_b64_tr_b16 v[170:171], v224 offset:0x1200
	ds_read_b64_tr_b16 v[172:173], v224 offset:0x1a00
	v_mfma_f32_32x32x16_bf16 v[0:15], v[154:157], v[174:177], v[0:15]
	ds_read_b64_tr_b16 v[174:175], v224 offset:0x2200
	ds_read_b64_tr_b16 v[176:177], v224 offset:0x2a00
	v_mfma_f32_32x32x16_bf16 v[0:15], v[158:161], v[178:181], v[0:15]
	ds_read_b64_tr_b16 v[178:179], v224 offset:0x3200
	ds_read_b64_tr_b16 v[180:181], v224 offset:0x3a00
	s_waitcnt vmcnt(4)
	v_add_u32_e32 v228, s4, v216
	ds_write_b128 v228, v[126:129]
	s_waitcnt lgkmcnt(1)
	v_mfma_f32_32x32x16_bf16 v[16:31], v[146:149], v[166:169], v[16:31]
	ds_read_b64_tr_b16 v[166:167], v224 offset:0x400
	ds_read_b64_tr_b16 v[168:169], v224 offset:0xc00
	v_mul_f32_e32 v196, 0xbe38aa3b, v213
	v_fmamk_f32 v80, v80, 0x3e38aa3b, v196
	v_fmamk_f32 v81, v81, 0x3e38aa3b, v196
	v_fmamk_f32 v82, v82, 0x3e38aa3b, v196
	v_mfma_f32_32x32x16_bf16 v[16:31], v[150:153], v[170:173], v[16:31]
	ds_read_b64_tr_b16 v[170:171], v224 offset:0x1400
	ds_read_b64_tr_b16 v[172:173], v224 offset:0x1c00
	v_fmamk_f32 v83, v83, 0x3e38aa3b, v196
	v_fmamk_f32 v84, v84, 0x3e38aa3b, v196
	v_fmamk_f32 v85, v85, 0x3e38aa3b, v196
	v_fmamk_f32 v86, v86, 0x3e38aa3b, v196
	v_mfma_f32_32x32x16_bf16 v[16:31], v[154:157], v[174:177], v[16:31]
	ds_read_b64_tr_b16 v[174:175], v224 offset:0x2400
	ds_read_b64_tr_b16 v[176:177], v224 offset:0x2c00
	v_fmamk_f32 v87, v87, 0x3e38aa3b, v196
	v_fmamk_f32 v88, v88, 0x3e38aa3b, v196
	v_fmamk_f32 v89, v89, 0x3e38aa3b, v196
	v_fmamk_f32 v90, v90, 0x3e38aa3b, v196
	v_mfma_f32_32x32x16_bf16 v[16:31], v[158:161], v[178:181], v[16:31]
	ds_read_b64_tr_b16 v[178:179], v224 offset:0x3400
	ds_read_b64_tr_b16 v[180:181], v224 offset:0x3c00
	v_fmamk_f32 v91, v91, 0x3e38aa3b, v196
	v_fmamk_f32 v92, v92, 0x3e38aa3b, v196
	v_fmamk_f32 v93, v93, 0x3e38aa3b, v196
	v_fmamk_f32 v94, v94, 0x3e38aa3b, v196
	v_add_u32_e32 v228, s4, v217
	ds_write_b128 v228, v[122:125]
	s_waitcnt lgkmcnt(1)
	v_mfma_f32_32x32x16_bf16 v[32:47], v[146:149], v[166:169], v[32:47]
	ds_read_b64_tr_b16 v[166:167], v224 offset:0x600
	ds_read_b64_tr_b16 v[168:169], v224 offset:0xe00
	v_fmamk_f32 v95, v95, 0x3e38aa3b, v196
	v_fmamk_f32 v197, v70, 0x3e38aa3b, v196
	v_fmamk_f32 v198, v71, 0x3e38aa3b, v196
	v_fmamk_f32 v199, v72, 0x3e38aa3b, v196
	v_mfma_f32_32x32x16_bf16 v[32:47], v[150:153], v[170:173], v[32:47]
	ds_read_b64_tr_b16 v[170:171], v224 offset:0x1600
	ds_read_b64_tr_b16 v[172:173], v224 offset:0x1e00
	v_fmamk_f32 v200, v73, 0x3e38aa3b, v196
	v_fmamk_f32 v201, v74, 0x3e38aa3b, v196
	v_fmamk_f32 v202, v75, 0x3e38aa3b, v196
	v_fmamk_f32 v203, v76, 0x3e38aa3b, v196
	v_mfma_f32_32x32x16_bf16 v[32:47], v[154:157], v[174:177], v[32:47]
	ds_read_b64_tr_b16 v[174:175], v224 offset:0x2600
	ds_read_b64_tr_b16 v[176:177], v224 offset:0x2e00
	v_fmamk_f32 v204, v77, 0x3e38aa3b, v196
	v_fmamk_f32 v205, v78, 0x3e38aa3b, v196
	v_mfma_f32_32x32x16_bf16 v[32:47], v[158:161], v[178:181], v[32:47]
	ds_read_b64_tr_b16 v[178:179], v224 offset:0x3600
	ds_read_b64_tr_b16 v[180:181], v224 offset:0x3e00
	v_add_u32_e32 v228, s4, v221
	ds_write_b128 v228, v[118:121] offset:49152
	s_waitcnt lgkmcnt(1)
	v_mfma_f32_32x32x16_bf16 v[48:63], v[146:149], v[166:169], v[48:63]
	v_add_u32_e32 v228, s4, v222
	ds_write_b128 v228, v[114:117] offset:49152
	v_exp_f32_e32 v146, v80
	v_exp_f32_e32 v147, v81
	v_exp_f32_e32 v148, v84
	v_exp_f32_e32 v149, v85
	v_mfma_f32_32x32x16_bf16 v[48:63], v[150:153], v[170:173], v[48:63]
	v_exp_f32_e32 v150, v88
	v_exp_f32_e32 v151, v89
	v_exp_f32_e32 v152, v92
	v_exp_f32_e32 v153, v93
	v_mfma_f32_32x32x16_bf16 v[48:63], v[154:157], v[174:177], v[48:63]
	v_exp_f32_e32 v154, v94
	v_exp_f32_e32 v155, v95
	v_exp_f32_e32 v156, v90
	v_exp_f32_e32 v157, v91
	v_fmamk_f32 v174, v64, 0x3e38aa3b, v196
	v_fmamk_f32 v175, v65, 0x3e38aa3b, v196
	v_mfma_f32_32x32x16_bf16 v[48:63], v[158:161], v[178:181], v[48:63]
	v_exp_f32_e32 v158, v86
	v_exp_f32_e32 v159, v87
	v_exp_f32_e32 v160, v82
	v_exp_f32_e32 v161, v83
	v_fmamk_f32 v178, v66, 0x3e38aa3b, v196
	v_fmamk_f32 v179, v67, 0x3e38aa3b, v196
	v_fmamk_f32 v180, v68, 0x3e38aa3b, v196
	v_fmamk_f32 v181, v69, 0x3e38aa3b, v196
	v_fmac_f32_e32 v196, 0x3e38aa3b, v79
	s_waitcnt lgkmcnt(0)
	s_barrier
; #define SBAR() __builtin_amdgcn_sched_barrier(0)
; #define RESC(a) do { if (__any((a) < 1.f)) { if (hi == 0) al_l[r32] = (a); asm volatile("s_waitcnt lgkmcnt(0)" ::: "memory"); \
;     _Pragma("unroll") for (int d = 0; d < 4; ++d) _Pragma("unroll") for (int r = 0; r < 16; ++r) o[d][r] *= al_l[crow(r, hi)]; } } while (0)
; __device__ __forceinline__ void da_finish2(f32x16& p0, f32x16& p1, float& m_reg, float& l_reg, float& alpha,
;                                            bf16x8& pa0, bf16x8& pa1, bf16x8& pa2, bf16x8& pa3) {
;     ...
;   for (int r = 0; r < 16; ++r) p1[r] = __builtin_amdgcn_exp2f(p1[r]);
;   float ps = 0.f;
; #pragma unroll
;   for (int r = 0; r < 16; ++r) ps += p0[r];
; #pragma unroll
;   for (int r = 0; r < 16; ++r) ps += p1[r];
;   { auto rr = __builtin_amdgcn_permlane32_swap(__float_as_uint(ps), __float_as_uint(ps), false, false);
;     ps = __uint_as_float(rr[0]) + __uint_as_float(rr[1]); }
;   alpha = 1.f;
;   if (__builtin_expect(!__all(ps < DA_BIG), 0)) {
; __device__ __forceinline__ void diff_block(const Params& p, int s, int h, int qb, char* lds, float lam_full, u16* Odst) {
;     ...
;     SBAR(); da_qkt(pA0, pA1, K_lds + cK, qr, r32, hi, cbyte0);
;     da_finish2(pB0, pB1, m_reg, l_reg, alB, pa0, pa1, pa2, pa3); SBAR();
;     RESC(alB);
	v_add_u32_e32 v68, s4, v223
	ds_read_b128 v[64:67], v68 offset:49152
	ds_read_b128 v[68:71], v68 offset:57344
	v_add_u32_e32 v170, s4, v220
	ds_read_b128 v[166:169], v170 offset:49152
	ds_read_b128 v[170:173], v170 offset:57344
	v_exp_f32_e32 v176, v174
	s_waitcnt lgkmcnt(3)
	v_mfma_f32_32x32x16_bf16 v[80:95], v[64:67], v[110:113], 0
	v_exp_f32_e32 v177, v175
	v_exp_f32_e32 v182, v178
	v_exp_f32_e32 v183, v179
	v_exp_f32_e32 v180, v180
	v_exp_f32_e32 v181, v181
	v_exp_f32_e32 v178, v197
	v_exp_f32_e32 v179, v198
	s_waitcnt lgkmcnt(2)
	v_mfma_f32_32x32x16_bf16 v[64:79], v[68:71], v[110:113], 0
	v_exp_f32_e32 v174, v199
	v_exp_f32_e32 v175, v200
	s_waitcnt lgkmcnt(1)
	v_mfma_f32_32x32x16_bf16 v[80:95], v[166:169], v[106:109], v[80:95]
	s_waitcnt lgkmcnt(0)
	v_mfma_f32_32x32x16_bf16 v[64:79], v[170:173], v[106:109], v[64:79]
	v_add_u32_e32 v170, s4, v219
	ds_read_b128 v[166:169], v170 offset:49152
	ds_read_b128 v[170:173], v170 offset:57344
	s_waitcnt lgkmcnt(1)
	v_mfma_f32_32x32x16_bf16 v[80:95], v[166:169], v[102:105], v[80:95]
	s_waitcnt lgkmcnt(0)
	v_mfma_f32_32x32x16_bf16 v[64:79], v[170:173], v[102:105], v[64:79]
	v_add_u32_e32 v170, s4, v218
	ds_read_b128 v[166:169], v170 offset:49152
	ds_read_b128 v[170:173], v170 offset:57344
	s_waitcnt lgkmcnt(1)
	v_mfma_f32_32x32x16_bf16 v[80:95], v[166:169], v[98:101], v[80:95]
	v_add_f32_e32 v166, 0, v146
	v_add_f32_e32 v166, v147, v166
	v_add_f32_e32 v166, v160, v166
	v_add_f32_e32 v166, v161, v166
	v_add_f32_e32 v166, v148, v166
	v_add_f32_e32 v166, v149, v166
	v_add_f32_e32 v166, v158, v166
	v_add_f32_e32 v166, v159, v166
	v_add_f32_e32 v166, v150, v166
	v_add_f32_e32 v166, v151, v166
	v_add_f32_e32 v166, v156, v166
	v_add_f32_e32 v166, v157, v166
	v_add_f32_e32 v166, v152, v166
	v_add_f32_e32 v166, v153, v166
	v_add_f32_e32 v166, v154, v166
	v_add_f32_e32 v166, v155, v166
	v_add_f32_e32 v166, v176, v166
	v_add_f32_e32 v166, v177, v166
	v_add_f32_e32 v166, v182, v166
	v_add_f32_e32 v166, v183, v166
	v_add_f32_e32 v166, v180, v166
	v_add_f32_e32 v166, v181, v166
	s_waitcnt lgkmcnt(0)
	v_mfma_f32_32x32x16_bf16 v[64:79], v[170:173], v[98:101], v[64:79]
	v_exp_f32_e32 v172, v201
	v_add_f32_e32 v166, v178, v166
	v_exp_f32_e32 v173, v202
	v_add_f32_e32 v166, v179, v166
	v_exp_f32_e32 v170, v203
	v_add_f32_e32 v166, v174, v166
	v_exp_f32_e32 v171, v204
	v_add_f32_e32 v166, v175, v166
	v_exp_f32_e32 v168, v205
	v_add_f32_e32 v166, v172, v166
	v_exp_f32_e32 v169, v196
	v_add_f32_e32 v166, v173, v166
	v_add_f32_e32 v166, v170, v166
	v_add_f32_e32 v166, v171, v166
	v_add_f32_e32 v166, v168, v166
	v_add_f32_e32 v225, v169, v166
	v_cmp_gt_f32_e32 vcc, s34, v225
	s_cmp_eq_u64 vcc, exec
	s_cbranch_scc0 .LBB0_255
	v_mov_b32_e32 v166, 1.0

; #define SBAR() __builtin_amdgcn_sched_barrier(0)
; #define RESC(a) do { if (__any((a) < 1.f)) { if (hi == 0) al_l[r32] = (a); asm volatile("s_waitcnt lgkmcnt(0)" ::: "memory"); \
;     _Pragma("unroll") for (int d = 0; d < 4; ++d) _Pragma("unroll") for (int r = 0; r < 16; ++r) o[d][r] *= al_l[crow(r, hi)]; } } while (0)
; __device__ __forceinline__ void da_finish2(f32x16& p0, f32x16& p1, float& m_reg, float& l_reg, float& alpha,
;                                            bf16x8& pa0, bf16x8& pa1, bf16x8& pa2, bf16x8& pa3) {
;     ...
;   for (int r = 0; r < 16; ++r) p1[r] = __builtin_amdgcn_exp2f(p1[r]);
;   float ps = 0.f;
; #pragma unroll
;   for (int r = 0; r < 16; ++r) ps += p0[r];
; #pragma unroll
;   for (int r = 0; r < 16; ++r) ps += p1[r];
;   { auto rr = __builtin_amdgcn_permlane32_swap(__float_as_uint(ps), __float_as_uint(ps), false, false);
;     ps = __uint_as_float(rr[0]) + __uint_as_float(rr[1]); }
;   alpha = 1.f;
;   if (__builtin_expect(!__all(ps < DA_BIG), 0)) {
; __device__ __forceinline__ void diff_block(const Params& p, int s, int h, int qb, char* lds, float lam_full, u16* Odst) {
;     ...
;   SBAR(); da_qkt(pB0, pB1, K_lds + cK, qr, r32, hi, cbyte0);
;   da_finish2(pA0, pA1, m_reg, l_reg, alA, pa0, pa1, pa2, pa3); SBAR();
;   RESC(alA);
;   da_pv(o, vb0 + pV, pa0, pa1, pa2, pa3); da_partial2(pB0, pB1, m_reg);
;   da_finish2(pB0, pB1, m_reg, l_reg, alB, pa0, pa1, pa2, pa3); SBAR();
.LBB0_256:
	v_add_u32_e32 v68, s10, v223
	ds_read_b128 v[64:67], v68 offset:49152
	ds_read_b128 v[68:71], v68 offset:57344
	v_add_u32_e32 v114, s10, v220
	v_exp_f32_e32 v122, v172
	v_exp_f32_e32 v123, v173
	s_waitcnt lgkmcnt(1)
	v_mfma_f32_32x32x16_bf16 v[80:95], v[64:67], v[110:113], 0
	v_exp_f32_e32 v120, v174
	v_exp_f32_e32 v121, v175
	v_exp_f32_e32 v118, v168
	v_exp_f32_e32 v119, v169
	s_waitcnt lgkmcnt(0)
	v_mfma_f32_32x32x16_bf16 v[64:79], v[68:71], v[110:113], 0
	ds_read_b128 v[110:113], v114 offset:49152
	ds_read_b128 v[114:117], v114 offset:57344
	s_waitcnt lgkmcnt(1)
	v_mfma_f32_32x32x16_bf16 v[80:95], v[110:113], v[106:109], v[80:95]
	v_add_u32_e32 v110, s10, v219
	s_waitcnt lgkmcnt(0)
	v_mfma_f32_32x32x16_bf16 v[64:79], v[114:117], v[106:109], v[64:79]
	ds_read_b128 v[106:109], v110 offset:49152
	ds_read_b128 v[110:113], v110 offset:57344
	v_exp_f32_e32 v116, v164
	v_exp_f32_e32 v117, v165
	s_waitcnt lgkmcnt(1)
	v_mfma_f32_32x32x16_bf16 v[80:95], v[106:109], v[102:105], v[80:95]
	v_add_u32_e32 v106, s10, v218
	s_waitcnt lgkmcnt(0)
	v_mfma_f32_32x32x16_bf16 v[64:79], v[110:113], v[102:105], v[64:79]
	ds_read_b128 v[102:105], v106 offset:49152
	ds_read_b128 v[106:109], v106 offset:57344
	v_exp_f32_e32 v110, v170
	v_exp_f32_e32 v111, v171
	v_exp_f32_e32 v112, v166
	v_exp_f32_e32 v113, v167
	s_waitcnt lgkmcnt(1)
	v_mfma_f32_32x32x16_bf16 v[80:95], v[102:105], v[98:101], v[80:95]
	s_waitcnt lgkmcnt(0)
	v_mfma_f32_32x32x16_bf16 v[64:79], v[106:109], v[98:101], v[64:79]
	v_add_f32_e32 v98, 0, v146
	v_add_f32_e32 v98, v147, v98
	v_add_f32_e32 v98, v148, v98
	v_add_f32_e32 v98, v149, v98
	v_add_f32_e32 v98, v150, v98
	v_add_f32_e32 v98, v151, v98
	v_add_f32_e32 v98, v160, v98
	v_add_f32_e32 v98, v161, v98
	v_add_f32_e32 v98, v158, v98
	v_add_f32_e32 v98, v159, v98
	v_add_f32_e32 v98, v156, v98
	v_add_f32_e32 v98, v157, v98
	v_exp_f32_e32 v106, v176
	v_add_f32_e32 v98, v152, v98
	v_exp_f32_e32 v107, v177
	v_add_f32_e32 v98, v153, v98
	v_add_f32_e32 v98, v154, v98
	v_add_f32_e32 v98, v155, v98
	v_exp_f32_e32 v108, v178
	v_add_f32_e32 v98, v106, v98
	v_exp_f32_e32 v109, v179
	v_add_f32_e32 v98, v107, v98
	v_add_f32_e32 v98, v122, v98
	v_add_f32_e32 v98, v123, v98
	v_add_f32_e32 v98, v108, v98
	v_add_f32_e32 v98, v109, v98
	v_add_f32_e32 v98, v120, v98
	v_add_f32_e32 v98, v121, v98
	v_add_f32_e32 v98, v110, v98
	v_add_f32_e32 v98, v111, v98
	v_add_f32_e32 v98, v118, v98
	v_add_f32_e32 v98, v119, v98
	v_add_f32_e32 v98, v112, v98
	v_add_f32_e32 v98, v113, v98
	v_add_f32_e32 v98, v116, v98
	v_add_f32_e32 v115, v117, v98
	v_cmp_gt_f32_e32 vcc, s34, v115
	s_cmp_eq_u64 vcc, exec
	s_cbranch_scc0 .LBB0_275
	v_mov_b32_e32 v114, 1.0

; #define SBAR() __builtin_amdgcn_sched_barrier(0)
; template <int D0> __device__ __forceinline__ void pv_one(f32x16& od, int vb, bf16x8 pa0, bf16x8 pa1, bf16x8 pa2, bf16x8 pa3) {
;   const s16x4 l0 = tr_read<v_rd_off(D0, 0, 0)>(vb), h0 = tr_read<v_rd_off(D0, 0, 1)>(vb), l1 = tr_read<v_rd_off(D0, 1, 0)>(vb), h1 = tr_read<v_rd_off(D0, 1, 1)>(vb);
;   const s16x4 l2 = tr_read<v_rd_off(D0, 2, 0)>(vb), h2 = tr_read<v_rd_off(D0, 2, 1)>(vb), l3 = tr_read<v_rd_off(D0, 3, 0)>(vb), h3 = tr_read<v_rd_off(D0, 3, 1)>(vb);
;   asm volatile("s_waitcnt lgkmcnt(0)" ::: "memory"); SBAR();
;     ...
;   od = __builtin_amdgcn_mfma_f32_32x32x16_bf16(pa0, PK(l0, h0), od, 0, 0, 0);
;   od = __builtin_amdgcn_mfma_f32_32x32x16_bf16(pa1, PK(l1, h1), od, 0, 0, 0);
;   od = __builtin_amdgcn_mfma_f32_32x32x16_bf16(pa2, PK(l2, h2), od, 0, 0, 0);
;   od = __builtin_amdgcn_mfma_f32_32x32x16_bf16(pa3, PK(l3, h3), od, 0, 0, 0);
; __device__ __forceinline__ void da_partial2(f32x16& p0, f32x16& p1, float m_reg) {
;   constexpr float C = DA_SCALE * 1.4426950408889634f;
;   const float mnC = -m_reg * C;
; #pragma unroll
;   for (int r = 0; r < 16; ++r) p0[r] = fmaf(p0[r], C, mnC);
; #pragma unroll
;   for (int r = 0; r < 16; ++r) p1[r] = fmaf(p1[r], C, mnC);
; #pragma unroll
;   for (int r = 0; r < 16; ++r) p0[r] = __builtin_amdgcn_exp2f(p0[r]);
; }
; __device__ __forceinline__ void da_finish2(f32x16& p0, f32x16& p1, float& m_reg, float& l_reg, float& alpha,
;                                            bf16x8& pa0, bf16x8& pa1, bf16x8& pa2, bf16x8& pa3) {
;   constexpr float C = DA_SCALE * 1.4426950408889634f;
; #pragma unroll
;   for (int r = 0; r < 16; ++r) p1[r] = __builtin_amdgcn_exp2f(p1[r]);
;   float ps = 0.f;
; #pragma unroll
;   for (int r = 0; r < 16; ++r) ps += p0[r];
; #pragma unroll
;   for (int r = 0; r < 16; ++r) ps += p1[r];
;   { auto rr = __builtin_amdgcn_permlane32_swap(__float_as_uint(ps), __float_as_uint(ps), false, false);
;     ps = __uint_as_float(rr[0]) + __uint_as_float(rr[1]); }
;   alpha = 1.f;
;   if (__builtin_expect(!__all(ps < DA_BIG), 0)) {
; __device__ __forceinline__ void diff_block(const Params& p, int s, int h, int qb, char* lds, float lam_full, u16* Odst) {
;     ...
;   da_pv(o, vb0 + pV, pa0, pa1, pa2, pa3); da_partial2(pB0, pB1, m_reg);
;   da_finish2(pB0, pB1, m_reg, l_reg, alB, pa0, pa1, pa2, pa3); SBAR();
;   RESC(alB);
.LBB0_262:
	v_add_u32_e32 v132, s4, v214
	ds_read_b64_tr_b16 v[116:117], v132 offset:0
	ds_read_b64_tr_b16 v[118:119], v132 offset:0x800
	ds_read_b64_tr_b16 v[120:121], v132 offset:0x1000
	ds_read_b64_tr_b16 v[122:123], v132 offset:0x1800
	ds_read_b64_tr_b16 v[124:125], v132 offset:0x2000
	ds_read_b64_tr_b16 v[126:127], v132 offset:0x2800
	ds_read_b64_tr_b16 v[128:129], v132 offset:0x3000
	ds_read_b64_tr_b16 v[130:131], v132 offset:0x3800
	s_waitcnt lgkmcnt(0)
	s_nop 0
	v_mfma_f32_32x32x16_bf16 v[0:15], v[98:101], v[116:119], v[0:15]
	ds_read_b64_tr_b16 v[116:117], v132 offset:0x200
	ds_read_b64_tr_b16 v[118:119], v132 offset:0xa00
	v_mfma_f32_32x32x16_bf16 v[0:15], v[102:105], v[120:123], v[0:15]
	ds_read_b64_tr_b16 v[120:121], v132 offset:0x1200
	ds_read_b64_tr_b16 v[122:123], v132 offset:0x1a00
	v_mfma_f32_32x32x16_bf16 v[0:15], v[106:109], v[124:127], v[0:15]
	ds_read_b64_tr_b16 v[124:125], v132 offset:0x2200
	ds_read_b64_tr_b16 v[126:127], v132 offset:0x2a00
	v_mfma_f32_32x32x16_bf16 v[0:15], v[110:113], v[128:131], v[0:15]
	ds_read_b64_tr_b16 v[128:129], v132 offset:0x3200
	ds_read_b64_tr_b16 v[130:131], v132 offset:0x3a00
	s_waitcnt lgkmcnt(0)
	v_mfma_f32_32x32x16_bf16 v[16:31], v[98:101], v[116:119], v[16:31]
	ds_read_b64_tr_b16 v[116:117], v132 offset:0x400
	ds_read_b64_tr_b16 v[118:119], v132 offset:0xc00
	v_mfma_f32_32x32x16_bf16 v[16:31], v[102:105], v[120:123], v[16:31]
	ds_read_b64_tr_b16 v[120:121], v132 offset:0x1400
	ds_read_b64_tr_b16 v[122:123], v132 offset:0x1c00
	v_mfma_f32_32x32x16_bf16 v[16:31], v[106:109], v[124:127], v[16:31]
	ds_read_b64_tr_b16 v[124:125], v132 offset:0x2400
	ds_read_b64_tr_b16 v[126:127], v132 offset:0x2c00
	v_mfma_f32_32x32x16_bf16 v[16:31], v[110:113], v[128:131], v[16:31]
	ds_read_b64_tr_b16 v[128:129], v132 offset:0x3400
	ds_read_b64_tr_b16 v[130:131], v132 offset:0x3c00
	s_waitcnt lgkmcnt(0)
	v_mfma_f32_32x32x16_bf16 v[32:47], v[98:101], v[116:119], v[32:47]
	ds_read_b64_tr_b16 v[116:117], v132 offset:0x600
	ds_read_b64_tr_b16 v[118:119], v132 offset:0xe00
	v_mfma_f32_32x32x16_bf16 v[32:47], v[102:105], v[120:123], v[32:47]
	ds_read_b64_tr_b16 v[120:121], v132 offset:0x1600
	ds_read_b64_tr_b16 v[122:123], v132 offset:0x1e00
	v_mfma_f32_32x32x16_bf16 v[32:47], v[106:109], v[124:127], v[32:47]
	ds_read_b64_tr_b16 v[124:125], v132 offset:0x2600
	ds_read_b64_tr_b16 v[126:127], v132 offset:0x2e00
	v_mfma_f32_32x32x16_bf16 v[32:47], v[110:113], v[128:131], v[32:47]
	ds_read_b64_tr_b16 v[128:129], v132 offset:0x3600
	ds_read_b64_tr_b16 v[130:131], v132 offset:0x3e00
	s_waitcnt lgkmcnt(0)
	v_mfma_f32_32x32x16_bf16 v[48:63], v[98:101], v[116:119], v[48:63]
	v_mul_f32_e32 v100, 0xbe38aa3b, v213
	v_fmamk_f32 v80, v80, 0x3e38aa3b, v100
	v_fmamk_f32 v81, v81, 0x3e38aa3b, v100
	v_fmamk_f32 v82, v82, 0x3e38aa3b, v100
	v_fmamk_f32 v83, v83, 0x3e38aa3b, v100
	v_exp_f32_e32 v98, v82
	v_fmamk_f32 v84, v84, 0x3e38aa3b, v100
	v_mfma_f32_32x32x16_bf16 v[48:63], v[102:105], v[120:123], v[48:63]
	v_fmamk_f32 v105, v64, 0x3e38aa3b, v100
	v_exp_f32_e32 v64, v80
	v_exp_f32_e32 v99, v83
	v_fmamk_f32 v85, v85, 0x3e38aa3b, v100
	v_fmamk_f32 v86, v86, 0x3e38aa3b, v100
	v_add_f32_e32 v80, 0, v64
	v_fmamk_f32 v87, v87, 0x3e38aa3b, v100
	v_mfma_f32_32x32x16_bf16 v[48:63], v[106:109], v[124:127], v[48:63]
	v_fmamk_f32 v106, v65, 0x3e38aa3b, v100
	v_exp_f32_e32 v65, v81
	v_fmamk_f32 v107, v66, 0x3e38aa3b, v100
	v_exp_f32_e32 v66, v84
	v_fmamk_f32 v108, v67, 0x3e38aa3b, v100
	v_exp_f32_e32 v67, v85
	v_add_f32_e32 v80, v65, v80
	v_fmamk_f32 v103, v94, 0x3e38aa3b, v100
	v_exp_f32_e32 v94, v86
	v_add_f32_e32 v80, v98, v80
	v_fmamk_f32 v88, v88, 0x3e38aa3b, v100
	v_fmamk_f32 v104, v95, 0x3e38aa3b, v100
	v_exp_f32_e32 v95, v87
	v_add_f32_e32 v80, v99, v80
	v_fmamk_f32 v89, v89, 0x3e38aa3b, v100
	v_fmamk_f32 v109, v68, 0x3e38aa3b, v100
	v_exp_f32_e32 v68, v88
	v_add_f32_e32 v80, v66, v80
	v_mfma_f32_32x32x16_bf16 v[48:63], v[110:113], v[128:131], v[48:63]
	v_fmamk_f32 v90, v90, 0x3e38aa3b, v100
	v_fmamk_f32 v110, v69, 0x3e38aa3b, v100
	v_exp_f32_e32 v69, v89
	v_add_f32_e32 v80, v67, v80
	v_fmamk_f32 v91, v91, 0x3e38aa3b, v100
	v_fmamk_f32 v101, v92, 0x3e38aa3b, v100
	v_exp_f32_e32 v92, v90
	v_add_f32_e32 v80, v94, v80
	v_fmamk_f32 v102, v93, 0x3e38aa3b, v100
	v_exp_f32_e32 v93, v91
	v_add_f32_e32 v80, v95, v80
	v_fmamk_f32 v111, v70, 0x3e38aa3b, v100
	v_exp_f32_e32 v70, v101
	v_add_f32_e32 v80, v68, v80
	v_fmamk_f32 v112, v71, 0x3e38aa3b, v100
	v_exp_f32_e32 v71, v102
	v_add_f32_e32 v80, v69, v80
	v_exp_f32_e32 v90, v103
	v_add_f32_e32 v80, v92, v80
	v_exp_f32_e32 v91, v104
	v_add_f32_e32 v80, v93, v80
	v_fmamk_f32 v113, v72, 0x3e38aa3b, v100
	v_exp_f32_e32 v72, v105
	v_add_f32_e32 v80, v70, v80
	v_fmamk_f32 v116, v73, 0x3e38aa3b, v100
	v_exp_f32_e32 v73, v106
	v_add_f32_e32 v80, v71, v80
	v_exp_f32_e32 v88, v107
	v_add_f32_e32 v80, v90, v80
	v_exp_f32_e32 v89, v108
	v_add_f32_e32 v80, v91, v80
	v_fmamk_f32 v117, v74, 0x3e38aa3b, v100
	v_exp_f32_e32 v74, v109
	v_add_f32_e32 v80, v72, v80
	v_fmamk_f32 v118, v75, 0x3e38aa3b, v100
	v_exp_f32_e32 v75, v110
	v_add_f32_e32 v80, v73, v80
	v_exp_f32_e32 v86, v111
	v_add_f32_e32 v80, v88, v80
	v_exp_f32_e32 v87, v112
	v_add_f32_e32 v80, v89, v80
	v_fmamk_f32 v119, v76, 0x3e38aa3b, v100
	v_exp_f32_e32 v76, v113
	v_add_f32_e32 v80, v74, v80
	v_fmamk_f32 v120, v77, 0x3e38aa3b, v100
	v_exp_f32_e32 v77, v116
	v_add_f32_e32 v80, v75, v80
	v_exp_f32_e32 v84, v117
	v_add_f32_e32 v80, v86, v80
	v_exp_f32_e32 v85, v118
	v_add_f32_e32 v80, v87, v80
	v_fmamk_f32 v121, v78, 0x3e38aa3b, v100
	v_exp_f32_e32 v78, v119
	v_add_f32_e32 v80, v76, v80
	v_fmac_f32_e32 v100, 0x3e38aa3b, v79
	v_exp_f32_e32 v79, v120
	v_add_f32_e32 v80, v77, v80
	v_exp_f32_e32 v82, v121
	v_add_f32_e32 v80, v84, v80
	v_exp_f32_e32 v83, v100
	v_add_f32_e32 v80, v85, v80
	v_add_f32_e32 v80, v78, v80
	v_add_f32_e32 v80, v79, v80
	v_add_f32_e32 v80, v82, v80
	v_add_f32_e32 v81, v83, v80
	v_cmp_gt_f32_e32 vcc, s34, v81
	s_cmp_eq_u64 vcc, exec
	s_cbranch_scc0 .LBB0_276
	v_mov_b32_e32 v80, 1.0

; __device__ __forceinline__ int crow(int r, int hi) { return (r & 3) + 8 * (r >> 2) + 4 * hi; }
; __device__ __forceinline__ void diff_block(const Params& p, int s, int h, int qb, char* lds, float lam_full, u16* Odst) {
;     ...
;   da_pv(o, vb0 + cK, pa0, pa1, pa2, pa3);
;     ...
;   if (hi == 0) li_l[r32] = l_reg;
;   asm volatile("s_waitcnt lgkmcnt(0)" ::: "memory");
;   float rli[16];
; #pragma unroll
;   for (int r = 0; r < 16; ++r) rli[r] = __builtin_amdgcn_rcpf(li_l[crow(r, hi)]);
.LBB0_268:
	ds_read_b64_tr_b16 v[82:83], v224 offset:0
	ds_read_b64_tr_b16 v[84:85], v224 offset:0x800
	ds_read_b64_tr_b16 v[86:87], v224 offset:0x1000
	ds_read_b64_tr_b16 v[88:89], v224 offset:0x1800
	ds_read_b64_tr_b16 v[90:91], v224 offset:0x2000
	ds_read_b64_tr_b16 v[92:93], v224 offset:0x2800
	ds_read_b64_tr_b16 v[98:99], v224 offset:0x3000
	ds_read_b64_tr_b16 v[100:101], v224 offset:0x3800
	s_waitcnt lgkmcnt(0)
	s_nop 0
	v_mfma_f32_32x32x16_bf16 v[0:15], v[64:67], v[82:85], v[0:15]
	ds_read_b64_tr_b16 v[82:83], v224 offset:0x200
	ds_read_b64_tr_b16 v[84:85], v224 offset:0xa00
	v_mfma_f32_32x32x16_bf16 v[0:15], v[68:71], v[86:89], v[0:15]
	ds_read_b64_tr_b16 v[86:87], v224 offset:0x1200
	ds_read_b64_tr_b16 v[88:89], v224 offset:0x1a00
	v_mfma_f32_32x32x16_bf16 v[0:15], v[72:75], v[90:93], v[0:15]
	ds_read_b64_tr_b16 v[90:91], v224 offset:0x2200
	ds_read_b64_tr_b16 v[92:93], v224 offset:0x2a00
	v_mfma_f32_32x32x16_bf16 v[0:15], v[76:79], v[98:101], v[0:15]
	ds_read_b64_tr_b16 v[98:99], v224 offset:0x3200
	ds_read_b64_tr_b16 v[100:101], v224 offset:0x3a00
	s_waitcnt lgkmcnt(0)
	v_mfma_f32_32x32x16_bf16 v[16:31], v[64:67], v[82:85], v[16:31]
	ds_read_b64_tr_b16 v[82:83], v224 offset:0x400
	ds_read_b64_tr_b16 v[84:85], v224 offset:0xc00
	v_mfma_f32_32x32x16_bf16 v[16:31], v[68:71], v[86:89], v[16:31]
	ds_read_b64_tr_b16 v[86:87], v224 offset:0x1400
	ds_read_b64_tr_b16 v[88:89], v224 offset:0x1c00
	v_mfma_f32_32x32x16_bf16 v[16:31], v[72:75], v[90:93], v[16:31]
	ds_read_b64_tr_b16 v[90:91], v224 offset:0x2400
	ds_read_b64_tr_b16 v[92:93], v224 offset:0x2c00
	v_mfma_f32_32x32x16_bf16 v[16:31], v[76:79], v[98:101], v[16:31]
	ds_read_b64_tr_b16 v[98:99], v224 offset:0x3400
	ds_read_b64_tr_b16 v[100:101], v224 offset:0x3c00
	s_waitcnt lgkmcnt(0)
	v_mfma_f32_32x32x16_bf16 v[32:47], v[64:67], v[82:85], v[32:47]
	ds_read_b64_tr_b16 v[82:83], v224 offset:0x600
	ds_read_b64_tr_b16 v[84:85], v224 offset:0xe00
	v_mfma_f32_32x32x16_bf16 v[32:47], v[68:71], v[86:89], v[32:47]
	ds_read_b64_tr_b16 v[86:87], v224 offset:0x1600
	ds_read_b64_tr_b16 v[88:89], v224 offset:0x1e00
	v_mfma_f32_32x32x16_bf16 v[32:47], v[72:75], v[90:93], v[32:47]
	ds_read_b64_tr_b16 v[90:91], v224 offset:0x2600
	ds_read_b64_tr_b16 v[92:93], v224 offset:0x2e00
	v_mfma_f32_32x32x16_bf16 v[32:47], v[76:79], v[98:101], v[32:47]
	ds_read_b64_tr_b16 v[98:99], v224 offset:0x3600
	ds_read_b64_tr_b16 v[100:101], v224 offset:0x3e00
	s_waitcnt lgkmcnt(0)
	v_mfma_f32_32x32x16_bf16 v[48:63], v[64:67], v[82:85], v[48:63]
	v_mfma_f32_32x32x16_bf16 v[48:63], v[68:71], v[86:89], v[48:63]
	v_mfma_f32_32x32x16_bf16 v[48:63], v[72:75], v[90:93], v[48:63]
	v_mfma_f32_32x32x16_bf16 v[48:63], v[76:79], v[98:101], v[48:63]
	v_fmac_f32_e32 v115, v225, v114
	v_fmac_f32_e32 v81, v115, v80
	v_mov_b32_e32 v230, v81
	s_nop 1
	v_permlane32_swap_b32_e32 v81, v230
	v_add_f32_e32 v81, v81, v230
	s_and_saveexec_b64 s[0:1], s[6:7]
	ds_write_b32 v215, v81
	s_or_b64 exec, exec, s[0:1]
	s_waitcnt lgkmcnt(0)
	v_add_u32_e32 v76, v212, v96
	ds_read_b128 v[64:67], v76
	ds_read_b128 v[68:71], v76 offset:32
	ds_read_b128 v[72:75], v76 offset:64
	v_cmp_eq_u32_e32 vcc, 0, v211
	v_cmp_ne_u32_e64 s[0:1], 0, v211
	s_waitcnt lgkmcnt(2)
	v_rcp_f32_e32 v94, v66
	v_rcp_f32_e32 v92, v67
	s_waitcnt lgkmcnt(1)
	v_rcp_f32_e32 v90, v68
	v_rcp_f32_e32 v88, v69
	ds_read_b128 v[66:69], v76 offset:96
	v_rcp_f32_e32 v64, v64
	v_rcp_f32_e32 v98, v65
	v_rcp_f32_e32 v86, v70
	v_rcp_f32_e32 v84, v71
	s_waitcnt lgkmcnt(1)
	v_rcp_f32_e32 v80, v72
	v_rcp_f32_e32 v78, v73
	v_rcp_f32_e32 v74, v74
	v_rcp_f32_e32 v70, v75
	s_waitcnt lgkmcnt(0)
	v_rcp_f32_e32 v72, v66
	v_rcp_f32_e32 v82, v67
	v_rcp_f32_e32 v76, v68
	v_rcp_f32_e32 v96, v69
	s_barrier
	s_and_saveexec_b64 s[2:3], s[0:1]
	s_cbranch_execz .LBB0_272
; __device__ __forceinline__ int crow(int r, int hi) { return (r & 3) + 8 * (r >> 2) + 4 * hi; }
; __device__ __forceinline__ void diff_block(const Params& p, int s, int h, int qb, char* lds, float lam_full, u16* Odst) {
;     ...
;   if (map == 1) {
; #pragma unroll
;     for (int r = 0; r < 16; ++r)
; #pragma unroll
;       for (int d0 = 0; d0 < 4; ++d0) xch[(rg * 32 + crow(r, hi)) * 128 + d0 * 32 + r32] = o[d0][r] * rli[r];
;   }
	v_lshlrev_b32_e32 v65, 11, v209
	v_lshl_or_b32 v65, v207, 2, v65
	v_lshl_add_u32 v65, v210, 9, v65
	v_mul_f32_e32 v66, v0, v64
	v_mul_f32_e32 v67, v16, v64
	ds_write2_b32 v65, v66, v67 offset1:32
	v_mul_f32_e32 v66, v32, v64
	v_mul_f32_e32 v67, v48, v64
	ds_write2_b32 v65, v66, v67 offset0:64 offset1:96
	v_mul_f32_e32 v66, v1, v98
	v_mul_f32_e32 v67, v17, v98
	ds_write2_b32 v65, v66, v67 offset0:128 offset1:160
	v_mul_f32_e32 v66, v33, v98
	v_mul_f32_e32 v67, v49, v98
	ds_write2_b32 v65, v66, v67 offset0:192 offset1:224
	v_mul_f32_e32 v66, v2, v94
	v_mul_f32_e32 v67, v18, v94
	v_add_u32_e32 v68, 0x400, v65
	ds_write2_b32 v68, v66, v67 offset1:32
	v_mul_f32_e32 v66, v34, v94
	v_mul_f32_e32 v67, v50, v94
	ds_write2_b32 v68, v66, v67 offset0:64 offset1:96
	v_mul_f32_e32 v66, v3, v92
	v_mul_f32_e32 v67, v19, v92
	ds_write2_b32 v68, v66, v67 offset0:128 offset1:160
	v_mul_f32_e32 v66, v35, v92
	v_mul_f32_e32 v67, v51, v92
	ds_write2_b32 v68, v66, v67 offset0:192 offset1:224
	v_mul_f32_e32 v66, v4, v90
	v_mul_f32_e32 v67, v20, v90
	v_add_u32_e32 v68, 0x1000, v65
	ds_write2_b32 v68, v66, v67 offset1:32
	v_mul_f32_e32 v66, v36, v90
	v_mul_f32_e32 v67, v52, v90
	ds_write2_b32 v68, v66, v67 offset0:64 offset1:96
	v_mul_f32_e32 v66, v5, v88
	v_mul_f32_e32 v67, v21, v88
	ds_write2_b32 v68, v66, v67 offset0:128 offset1:160
	v_mul_f32_e32 v66, v37, v88
	v_mul_f32_e32 v67, v53, v88
	ds_write2_b32 v68, v66, v67 offset0:192 offset1:224
	v_mul_f32_e32 v66, v6, v86
	v_mul_f32_e32 v67, v22, v86
	v_add_u32_e32 v68, 0x1400, v65
	ds_write2_b32 v68, v66, v67 offset1:32
	v_mul_f32_e32 v66, v38, v86
	v_mul_f32_e32 v67, v54, v86
	ds_write2_b32 v68, v66, v67 offset0:64 offset1:96
	v_mul_f32_e32 v66, v7, v84
	v_mul_f32_e32 v67, v23, v84
	ds_write2_b32 v68, v66, v67 offset0:128 offset1:160
	v_mul_f32_e32 v66, v39, v84
	v_mul_f32_e32 v67, v55, v84
	ds_write2_b32 v68, v66, v67 offset0:192 offset1:224
	v_mul_f32_e32 v66, v8, v80
	v_mul_f32_e32 v67, v24, v80
	v_add_u32_e32 v68, 0x2000, v65
	ds_write2_b32 v68, v66, v67 offset1:32
	v_mul_f32_e32 v66, v40, v80
	v_mul_f32_e32 v67, v56, v80
	ds_write2_b32 v68, v66, v67 offset0:64 offset1:96
	v_mul_f32_e32 v66, v9, v78
	v_mul_f32_e32 v67, v25, v78
	ds_write2_b32 v68, v66, v67 offset0:128 offset1:160
	v_mul_f32_e32 v66, v41, v78
	v_mul_f32_e32 v67, v57, v78
	ds_write2_b32 v68, v66, v67 offset0:192 offset1:224
	v_mul_f32_e32 v66, v10, v74
	v_mul_f32_e32 v67, v26, v74
	v_add_u32_e32 v68, 0x2400, v65
	ds_write2_b32 v68, v66, v67 offset1:32
	v_mul_f32_e32 v66, v42, v74
	v_mul_f32_e32 v67, v58, v74
	ds_write2_b32 v68, v66, v67 offset0:64 offset1:96
	v_mul_f32_e32 v66, v11, v70
	v_mul_f32_e32 v67, v27, v70
	ds_write2_b32 v68, v66, v67 offset0:128 offset1:160
	v_mul_f32_e32 v66, v43, v70
	v_mul_f32_e32 v67, v59, v70
	ds_write2_b32 v68, v66, v67 offset0:192 offset1:224
	v_mul_f32_e32 v66, v12, v72
	v_mul_f32_e32 v67, v28, v72
	v_add_u32_e32 v68, 0x3000, v65
	ds_write2_b32 v68, v66, v67 offset1:32
	v_mul_f32_e32 v66, v44, v72
	v_mul_f32_e32 v67, v60, v72
	ds_write2_b32 v68, v66, v67 offset0:64 offset1:96
	v_mul_f32_e32 v66, v13, v82
	v_mul_f32_e32 v67, v29, v82
	ds_write2_b32 v68, v66, v67 offset0:128 offset1:160
	v_mul_f32_e32 v66, v45, v82
	v_mul_f32_e32 v67, v61, v82
	ds_write2_b32 v68, v66, v67 offset0:192 offset1:224
	v_mul_f32_e32 v66, v14, v76
	v_mul_f32_e32 v67, v30, v76
	v_add_u32_e32 v65, 0x3400, v65
	ds_write2_b32 v65, v66, v67 offset1:32
	v_mul_f32_e32 v66, v46, v76
	v_mul_f32_e32 v67, v62, v76
	ds_write2_b32 v65, v66, v67 offset0:64 offset1:96
	v_mul_f32_e32 v66, v15, v96
	v_mul_f32_e32 v67, v31, v96
	ds_write2_b32 v65, v66, v67 offset0:128 offset1:160
	v_mul_f32_e32 v66, v47, v96
	v_mul_f32_e32 v67, v63, v96
	ds_write2_b32 v65, v66, v67 offset0:192 offset1:224
